# work list of S5/decode phases re-dealt: waves 1-7 take two S5 units each, the decode wave takes the remainder after its decode unit
# speedup vs baseline: 1.0816x; 1.0047x over previous
; template <int MODE>
; __device__ __forceinline__ void s5_unit(const Params& P, unsigned char* wl, const int id) {
;     const int lane = threadIdx.x & 63, l16 = lane & 15, q = lane >> 4;
;     bf16_t* Btab = (bf16_t*)wl; float* buf = (float*)(wl + 4096); unsigned* Hw = (unsigned*)(wl + 4096 + 8320); bf16_t* Ub = Btab;
;     const bf16_t* PROJ = (const bf16_t*)(P.ws + O_PROJ); bf16_t* G = (bf16_t*)(P.ws + O_G);
;     int g, row0, nblk, slot = 0, b = 0, c = 0, sb = 0;
; __global__ void __launch_bounds__(512, 2) fwd(Params P) {
;     ...
;         for (int r2 = 0; r2 < NREP(15); ++r2) for (int id = blockIdx.x * 8 + wave; id < 4672; id += gridDim.x * 8) {
;             if (id < 2048 && (id & 7) == 0) { mlstm_decode_wave(P, shm + wave * S5_WL, id >> 3); continue; }
;             const int sidx = id < 2048 ? id - (id >> 3) - 1 : 1792 + (id - 2048);
;             if (sidx < 3904) s5_unit<0>(P, shm + wave * S5_WL, sidx); else s5_unit<2>(P, shm + wave * S5_WL, sidx - 3904); }
.LBB0_343:
	v_lshl_add_u32 v151, s94, 3, v215
	s_lshl_b32 s0, s96, 3
	v_mov_b32_e32 v244, s0
	s_cmpk_eq_i32 s96, 0x100
	s_cselect_b64 s[0:1], -1, 0
	v_mov_b32_e32 v240, s94
	v_mul_u32_u24_e32 v241, 7, v240
	v_sub_u32_e32 v240, 0x7ff, v240
	v_sub_u32_e32 v241, 0xf00, v241
	v_cmp_eq_u32_e32 vcc, 0, v215
	v_mov_b32_e32 v242, 0x800
	v_mov_b32_e32 v243, 0x4000
	v_cndmask_b32_e32 v240, v240, v241, vcc
	v_cndmask_b32_e32 v242, v242, v243, vcc
	v_cndmask_b32_e64 v240, v244, v240, s[0:1]
	v_cndmask_b32_e64 v242, v244, v242, s[0:1]
	s_movk_i32 s0, 0x1240
	v_cmp_gt_i32_e32 vcc, s0, v151
	s_barrier
	s_and_saveexec_b64 s[16:17], vcc
	s_cbranch_execz .LBB0_376
	s_movk_i32 s0, 0x4200
	v_mad_u32_u24 v153, v215, s0, 0
	v_add_u32_e32 v0, 0x1000, v153
	v_cndmask_b32_e64 v2, v0, v153, s[4:5]
	v_lshrrev_b32_e32 v0, 1, v146
	v_and_b32_e32 v150, 8, v0
	v_lshrrev_b32_e32 v1, 4, v146
	v_lshl_add_u32 v2, v150, 1, v2
	v_lshlrev_b32_e32 v3, 5, v147
	v_mov_b32_e32 v0, 0
	v_add_u32_e32 v183, v2, v3
	v_mul_u32_u24_e32 v2, 0x820, v1
	v_add3_u32 v212, v153, v2, v64
	v_and_b32_e32 v2, 48, v146
	v_lshlrev_b32_e32 v4, 3, v146
	v_mov_b32_e32 v5, v0
	v_readlane_b32 s52, v245, 34
	v_add3_u32 v213, v153, v3, v2
	v_mul_u32_u24_e32 v3, 0x110, v147
	v_add_u32_e32 v218, v153, v4
	v_lshl_add_u64 v[4:5], s[12:13], 0, v[4:5]
	s_mov_b64 s[0:1], 0x1e5cb000
	v_lshlrev_b32_e32 v158, 4, v146
	v_mov_b32_e32 v159, v0
	v_readlane_b32 s56, v245, 38
	v_readlane_b32 s57, v245, 39
	v_readlane_b32 s58, v245, 40
	v_readlane_b32 s59, v245, 41
	v_readlane_b32 s60, v245, 42
	v_readlane_b32 s61, v245, 43
	v_readlane_b32 s62, v245, 44
	v_readlane_b32 s63, v245, 45
	v_readlane_b32 s64, v245, 46
	v_readlane_b32 s65, v245, 47
	v_readlane_b32 s66, v245, 48
	v_readlane_b32 s67, v245, 49
	v_add3_u32 v216, v153, v3, v2
	v_lshl_add_u64 v[156:157], v[4:5], 0, s[0:1]
	v_readlane_b32 s72, v245, 18
	v_lshl_add_u64 v[4:5], s[66:67], 0, v[158:159]
	v_and_b32_e32 v3, 0x1c0, v214
	v_readlane_b32 s56, v245, 2
	s_add_u32 s18, s12, 0x2100000
	v_readlane_b32 s73, v245, 19
	v_cmp_eq_u32_e64 s[6:7], 0, v3
	v_mov_b32_e32 v3, v0
	v_readlane_b32 s70, v245, 16
	v_readlane_b32 s71, v245, 17
	v_lshlrev_b32_e32 v152, 2, v1
	s_addc_u32 s19, s13, 0
	v_lshlrev_b32_e32 v1, 7, v1
	v_lshlrev_b32_e32 v154, 2, v146
	s_mov_b64 s[0:1], 0xc924040
	v_lshl_add_u64 v[166:167], s[70:71], 0, v[2:3]
	v_lshl_add_u64 v[168:169], s[72:73], 0, v[2:3]
	v_and_b32_e32 v2, 16, v146
	v_lshlrev_b32_e32 v6, 6, v147
	v_add3_u32 v217, v153, v1, v148
	v_sub_u32_e32 v1, 0, v154
	v_readlane_b32 s82, v245, 28
	v_readlane_b32 s83, v245, 29
	s_add_u32 s20, s12, 0x12dc2000
	v_readlane_b32 s53, v245, 35
	v_readlane_b32 s54, v245, 36
	v_readlane_b32 s55, v245, 37
	v_lshl_add_u64 v[164:165], v[4:5], 0, s[0:1]
	v_lshl_add_u64 v[2:3], s[12:13], 0, v[2:3]
	s_mov_b64 s[0:1], 0x458a000
	s_movk_i32 s25, 0x1000
	v_lshl_add_u32 v155, v146, 6, v153
	v_lshl_add_u64 v[160:161], s[46:47], 0, v[158:159]
	v_add_u32_e32 v219, v153, v158
	v_lshl_add_u64 v[162:163], s[82:83], 0, v[158:159]
	s_addc_u32 s21, s13, 0
	s_lshl_b32 s54, s96, 3
	v_lshl_add_u64 v[170:171], v[2:3], 0, s[0:1]
	s_mov_b64 s[22:23], 0
	s_mov_b32 s33, 0x3fb8aa3b
	s_mov_b32 s55, 0xc2ce8ed0
	s_mov_b32 s50, 0x42b17218
	s_brev_b32 s51, 18
	s_mov_b32 s93, 0xfe5163ab
	v_mov_b32_e32 v220, 0x3c0881c4
	v_mov_b32_e32 v221, 0xbab64f3b
	s_movk_i32 s89, 0x1f8
	v_lshlrev_b32_e32 v222, 2, v6
	s_movk_i32 s90, 0x4800
	s_movk_i32 s91, 0x7fff
	s_mov_b32 s92, 0x4524000
	s_mov_b32 s52, 0x4724000
	v_add_u32_e32 v223, v218, v1
	s_mov_b32 s53, 0x7060302
	s_mov_b32 s88, 0x88888889
	s_mov_b32 s24, 0x3d800000
	v_mov_b32_e32 v224, 0x3ecc95a3
	s_mov_b64 s[26:27], 0x8000
	v_mov_b32_e32 v225, 0x3727c5ac
	v_mov_b32_e32 v226, 0xffffff00
	v_mov_b32_e32 v227, 0x7f800000
	v_not_b32_e32 v228, 63
	v_not_b32_e32 v229, 31
	v_mov_b32_e32 v230, 0x7fc00000
	v_mov_b32_e32 v172, 0x3f317218
	v_mov_b32_e32 v231, 0xff800000
	v_readlane_b32 s74, v245, 20
	v_readlane_b32 s75, v245, 21
	v_readlane_b32 s76, v245, 22
	v_readlane_b32 s77, v245, 23
	v_readlane_b32 s78, v245, 24
	v_readlane_b32 s79, v245, 25
	v_readlane_b32 s80, v245, 26
	v_readlane_b32 s81, v245, 27
	v_readlane_b32 s84, v245, 30
	v_readlane_b32 s85, v245, 31
	v_readlane_b32 s86, v245, 32
	v_readlane_b32 s87, v245, 33
	v_readlane_b32 s57, v245, 3
	v_readlane_b32 s58, v245, 4
	v_readlane_b32 s59, v245, 5
	v_readlane_b32 s60, v245, 6
	v_readlane_b32 s61, v245, 7
	v_readlane_b32 s62, v245, 8
	v_readlane_b32 s63, v245, 9
	v_readlane_b32 s64, v245, 10
	v_readlane_b32 s65, v245, 11
	v_readlane_b32 s66, v245, 12
	v_readlane_b32 s67, v245, 13
	v_readlane_b32 s68, v245, 14
	v_readlane_b32 s69, v245, 15
	s_branch .LBB0_347

; template <int MODE>
; __device__ __forceinline__ void s5_unit(const Params& P, unsigned char* wl, const int id) {
;     const int lane = threadIdx.x & 63, l16 = lane & 15, q = lane >> 4;
;     bf16_t* Btab = (bf16_t*)wl; float* buf = (float*)(wl + 4096); unsigned* Hw = (unsigned*)(wl + 4096 + 8320); bf16_t* Ub = Btab;
;     const bf16_t* PROJ = (const bf16_t*)(P.ws + O_PROJ); bf16_t* G = (bf16_t*)(P.ws + O_G);
;     int g, row0, nblk, slot = 0, b = 0, c = 0, sb = 0;
; __global__ void __launch_bounds__(512, 2) fwd(Params P) {
;     ...
;         for (int r2 = 0; r2 < NREP(13); ++r2) for (int id = blockIdx.x * 8 + wave; id < 4352; id += gridDim.x * 8) {
;             if (id < 2048 && (id & 7) == 0) { mlstm_decode_wave(P, shm + wave * S5_WL, 256 + (id >> 3)); continue; }
;             s5_unit<1>(P, shm + wave * S5_WL, id < 2048 ? id - (id >> 3) - 1 : 1792 + (id - 2048)); }
.LBB0_439:
	s_or_b64 exec, exec, s[4:5]
	v_lshl_add_u32 v145, s94, 3, v215
	s_lshl_b32 s0, s96, 3
	v_mov_b32_e32 v244, s0
	s_cmpk_eq_i32 s96, 0x100
	s_cselect_b64 s[0:1], -1, 0
	v_mov_b32_e32 v240, s94
	v_mul_u32_u24_e32 v241, 7, v240
	v_sub_u32_e32 v240, 0x7ff, v240
	v_sub_u32_e32 v241, 0xf00, v241
	v_cmp_eq_u32_e32 vcc, 0, v215
	v_mov_b32_e32 v242, 0x4000
	v_mov_b32_e32 v243, 0x100
	v_cndmask_b32_e32 v240, v240, v241, vcc
	v_cndmask_b32_e32 v242, v242, v243, vcc
	v_cndmask_b32_e64 v240, v244, v240, s[0:1]
	v_cndmask_b32_e64 v242, v244, v242, s[0:1]
	s_movk_i32 s0, 0x1100
	v_cmp_gt_i32_e32 vcc, s0, v145
	s_and_saveexec_b64 s[16:17], vcc
	s_cbranch_execz .LBB0_469
	s_movk_i32 s0, 0x4200
	v_mad_u32_u24 v153, v215, s0, 0
	v_and_b32_e32 v144, 63, v214
	v_add_u32_e32 v0, 0x1000, v153
	s_add_u32 s18, s12, 0x4542000
	v_cmp_gt_u32_e64 s[2:3], 32, v144
	s_addc_u32 s19, s13, 0
	v_and_b32_e32 v157, 15, v214
	v_cndmask_b32_e64 v2, v0, v153, s[2:3]
	v_lshrrev_b32_e32 v0, 1, v214
	v_and_b32_e32 v0, 8, v0
	v_mov_b32_e32 v147, 0
	s_add_u32 s20, s12, 0x1e5cb000
	v_bfe_u32 v1, v214, 4, 2
	v_lshlrev_b32_e32 v3, 1, v0
	v_lshlrev_b32_e32 v4, 5, v157
	s_addc_u32 s21, s13, 0
	v_lshlrev_b32_e32 v148, 3, v144
	v_mov_b32_e32 v149, v147
	v_add3_u32 v216, v2, v3, v4
	v_lshl_add_u64 v[150:151], s[20:21], 0, v[148:149]
	v_mul_u32_u24_e32 v2, 0x820, v1
	v_lshlrev_b32_e32 v149, 2, v157
	v_lshlrev_b32_e32 v146, 1, v157
	v_add3_u32 v217, v153, v2, v149
	v_lshl_add_u64 v[2:3], s[12:13], 0, v[146:147]
	s_mov_b64 s[0:1], 0x2100000
	v_add_u32_e32 v5, v153, v146
	v_lshl_add_u64 v[154:155], v[2:3], 0, s[0:1]
	v_mul_u32_u24_e32 v2, 30, v157
	v_and_b32_e32 v146, 48, v214
	v_readlane_b32 s52, v245, 34
	v_add3_u32 v218, v5, v2, v146
	v_mul_u32_u24_e32 v2, 0x110, v157
	v_lshlrev_b32_e32 v158, 4, v144
	v_mov_b32_e32 v159, v147
	v_readlane_b32 s53, v245, 35
	v_readlane_b32 s54, v245, 36
	v_readlane_b32 s55, v245, 37
	v_readlane_b32 s56, v245, 38
	v_readlane_b32 s57, v245, 39
	v_readlane_b32 s58, v245, 40
	v_readlane_b32 s59, v245, 41
	v_readlane_b32 s60, v245, 42
	v_readlane_b32 s61, v245, 43
	v_readlane_b32 s62, v245, 44
	v_readlane_b32 s63, v245, 45
	v_readlane_b32 s64, v245, 46
	v_readlane_b32 s65, v245, 47
	v_readlane_b32 s66, v245, 48
	v_readlane_b32 s67, v245, 49
	v_add3_u32 v219, v153, v2, v146
	v_readlane_b32 s68, v245, 18
	v_lshl_add_u64 v[2:3], s[66:67], 0, v[158:159]
	v_readlane_b32 s52, v245, 2
	s_add_u32 s22, s12, 0x4500000
	v_readlane_b32 s69, v245, 19
	s_mov_b64 s[0:1], 0xc924040
	v_readlane_b32 s66, v245, 16
	v_readlane_b32 s67, v245, 17
	s_addc_u32 s23, s13, 0
	v_lshl_add_u64 v[164:165], v[2:3], 0, s[0:1]
	v_and_b32_e32 v2, 0x1c0, v214
	v_lshl_add_u64 v[166:167], s[66:67], 0, v[146:147]
	v_lshl_add_u64 v[168:169], s[68:69], 0, v[146:147]
	v_and_b32_e32 v146, 16, v214
	v_lshlrev_b32_e32 v156, 2, v144
	s_add_u32 s24, s12, 0x12dc2000
	v_cmp_eq_u32_e64 s[6:7], 0, v2
	v_lshl_add_u64 v[2:3], s[12:13], 0, v[146:147]
	s_mov_b64 s[0:1], 0x458a000
	v_lshlrev_b32_e32 v152, 2, v1
	v_lshlrev_b32_e32 v4, 6, v157
	v_lshlrev_b32_e32 v1, 7, v1
	v_add_u32_e32 v220, v153, v156
	v_mul_u32_u24_e32 v6, 12, v144
	v_readlane_b32 s78, v245, 28
	v_readlane_b32 s79, v245, 29
	s_addc_u32 s25, s13, 0
	v_lshl_add_u64 v[170:171], v[2:3], 0, s[0:1]
	s_lshl_b32 s0, s94, 3
	s_movk_i32 s29, 0x1000
	v_lshl_add_u32 v185, v144, 6, v153
	v_lshl_add_u64 v[160:161], s[46:47], 0, v[158:159]
	v_lshl_add_u64 v[162:163], s[78:79], 0, v[158:159]
	v_cmp_eq_u32_e64 s[4:5], 0, v144
	s_lshl_b32 s33, s96, 3
	v_add_u16_e32 v221, s0, v215
	s_mov_b64 s[26:27], 0
	s_mov_b32 s42, 0x3fb8aa3b
	s_mov_b32 s43, 0xc2ce8ed0
	s_mov_b32 s46, 0x42b17218
	v_mov_b32_e32 v222, 0x3c0881c4
	v_mov_b32_e32 v223, 0xbab64f3b
	v_lshlrev_b32_e32 v224, 2, v4
	s_movk_i32 s47, 0x7fff
	s_movk_i32 s50, 0x4800
	v_lshlrev_b32_e32 v172, 1, v0
	s_mov_b32 s51, 0x7060302
	v_add_u32_e32 v225, v220, v6
	v_mov_b32_e32 v226, 0x3ecc95a3
	v_mov_b32_e32 v227, 0x3727c5ac
	v_mov_b32_e32 v228, 0xffffff00
	v_mov_b32_e32 v229, 0x7f800000
	v_not_b32_e32 v230, 63
	v_not_b32_e32 v231, 31
	v_mov_b32_e32 v232, 0x7fc00000
	v_add_u32_e32 v233, v5, v1
	v_mov_b32_e32 v174, 0x3f317218
	v_mov_b32_e32 v234, 0xff800000
	s_mov_b32 s28, 0x3d800000
	s_mov_b64 s[30:31], 0x8000
	v_readlane_b32 s70, v245, 20
	v_readlane_b32 s71, v245, 21
	v_readlane_b32 s72, v245, 22
	v_readlane_b32 s73, v245, 23
	v_readlane_b32 s74, v245, 24
	v_readlane_b32 s75, v245, 25
	v_readlane_b32 s76, v245, 26
	v_readlane_b32 s77, v245, 27
	v_readlane_b32 s80, v245, 30
	v_readlane_b32 s81, v245, 31
	v_readlane_b32 s82, v245, 32
	v_readlane_b32 s83, v245, 33
	v_readlane_b32 s53, v245, 3
	v_readlane_b32 s54, v245, 4
	v_readlane_b32 s55, v245, 5
	v_readlane_b32 s56, v245, 6
	v_readlane_b32 s57, v245, 7
	v_readlane_b32 s58, v245, 8
	v_readlane_b32 s59, v245, 9
	v_readlane_b32 s60, v245, 10
	v_readlane_b32 s61, v245, 11
	v_readlane_b32 s62, v245, 12
	v_readlane_b32 s63, v245, 13
	v_readlane_b32 s64, v245, 14
	v_readlane_b32 s65, v245, 15
	s_branch .LBB0_443
